# pool epilogue gate loads batched; attention staging counted vmcnt; prep table copy batched + RoPE/V-transpose warm-up loops
# speedup vs baseline: 1.0035x; 1.0003x over previous
.LBB0_483:
	s_and_b64 vcc, exec, s[0:1]
	s_cbranch_vccz .LBB0_822
	s_and_b64 vcc, exec, s[36:37]
	s_cbranch_vccnz .LBB0_509
	s_mov_b64 s[24:25], s[66:67]
	s_mov_b64 s[0:1], s[64:65]
	v_mov_b32_e32 v205, v204
	v_readlane_b32 s0, v254, 25
	v_readlane_b32 s1, v254, 26
	s_andn2_b64 vcc, exec, s[0:1]
	s_cbranch_vccnz .LBB0_487
	s_add_u32 s0, s24, 0x1de88000
	s_addc_u32 s1, s25, 0
	v_lshl_add_u32 v0, v205, 4, 0
	global_load_dwordx4 v[2:5], v0, s[0:1]
	v_add_u32_e32 v34, 0x2000, v0
	global_load_dwordx4 v[6:9], v34, s[0:1]
	v_add_u32_e32 v34, 0x4000, v0
	global_load_dwordx4 v[10:13], v34, s[0:1]
	v_add_u32_e32 v34, 0x6000, v0
	global_load_dwordx4 v[14:17], v34, s[0:1]
	v_add_u32_e32 v34, 0x8000, v0
	global_load_dwordx4 v[18:21], v34, s[0:1]
	v_add_u32_e32 v34, 0xa000, v0
	global_load_dwordx4 v[22:25], v34, s[0:1]
	v_add_u32_e32 v34, 0xc000, v0
	global_load_dwordx4 v[26:29], v34, s[0:1]
	v_add_u32_e32 v34, 0xe000, v0
	global_load_dwordx4 v[30:33], v34, s[0:1]
	s_waitcnt vmcnt(0)
	ds_write_b128 v0, v[2:5]
	ds_write_b128 v0, v[6:9] offset:8192
	ds_write_b128 v0, v[10:13] offset:16384
	ds_write_b128 v0, v[14:17] offset:24576
	ds_write_b128 v0, v[18:21] offset:32768
	ds_write_b128 v0, v[22:25] offset:40960
	ds_write_b128 v0, v[26:29] offset:49152
	ds_write_b128 v0, v[30:33] offset:57344
	s_waitcnt lgkmcnt(0)
	s_barrier

.LBB0_502:
	s_or_b64 exec, exec, s[0:1]
	s_mov_b32 s0, 0x80000
	v_cmp_gt_i32_e32 vcc, s0, v164
	s_mov_b64 s[0:1], exec
	s_and_b64 s[18:19], s[0:1], vcc
	v_mov_b32_e32 v234, 1
	v_mov_b64_e32 v[236:237], 0x3bf
	v_mov_b64_e32 v[238:239], 0x3c0
	v_mov_b32_e32 v26, 0xfffff800
	v_mov_b32_e32 v27, 0xffffff00
	v_mov_b32_e32 v235, 0x80
	v_mov_b32_e32 v240, 0xbcb504f3
	v_mov_b32_e32 v241, 0x3cb504f3
	v_mov_b64_e32 v[242:243], 0x17f
	v_mov_b64_e32 v[244:245], 0x180
	s_mov_b64 exec, s[18:19]
	s_cbranch_execz .LBB0_505
	v_readlane_b32 s18, v254, 44
	s_lshl_b32 s19, s39, 13
	s_mov_b64 s[28:29], 0
	v_lshl_add_u32 v2, v205, 3, s18
	s_lshl_b32 s18, s39, 12
	v_mov_b32_e32 v3, v164
	v_mov_b32_e32 v30, v3
	v_mov_b32_e32 v31, v2
	v_mov_b32_e32 v32, v165
.Lrope_warm:
	v_bfe_u32 v6, v30, 2, 1
	v_ashrrev_i32_e32 v0, 7, v30
	v_add_u32_e32 v0, 0x2000, v0
	v_mov_b64_e32 v[4:5], s[36:37]
	v_mad_i64_i32 v[4:5], s[22:23], v0, s77, v[4:5]
	v_and_b32_e32 v0, 0x780, v32
	v_lshlrev_b32_e32 v0, 1, v0
	v_lshl_add_u64 v[4:5], v[4:5], 0, v[0:1]
	v_lshlrev_b32_e32 v0, 7, v6
	v_and_b32_e32 v25, 24, v31
	v_lshl_add_u64 v[4:5], v[4:5], 0, v[0:1]
	v_lshlrev_b32_e32 v0, 1, v25
	v_lshl_add_u64 v[12:13], v[4:5], 0, v[0:1]
	global_load_dword v33, v[12:13], off
	global_load_dword v34, v[12:13], off offset:64
	v_add_u32_e32 v30, s38, v30
	s_mov_b32 s22, 0x7ffff
	v_cmp_lt_i32_e32 vcc, s22, v30
	v_add_u32_e32 v31, s18, v31
	v_add_u32_e32 v32, s19, v32
	s_or_b64 s[28:29], vcc, s[28:29]
	s_andn2_b64 exec, exec, s[28:29]
	s_cbranch_execnz .Lrope_warm
	s_mov_b64 exec, s[0:1]
	s_mov_b32 s22, 0x80000
	v_cmp_gt_i32_e32 vcc, s22, v164
	s_mov_b64 s[28:29], 0
	s_nop 1
	s_and_b64 exec, exec, vcc

.LBB0_505:
	s_or_b64 exec, exec, s[0:1]
	s_mov_b32 s0, 0xc0000
	v_cmp_gt_i32_e32 vcc, s0, v164
	s_and_saveexec_b64 s[28:29], vcc
	s_movk_i32 s18, 0x6000
	s_movk_i32 s19, 0x3000
	s_mov_b32 s22, 0x10000
	s_cbranch_execz .LBB0_508
	s_add_u32 s24, s24, 0x1a848000
	s_addc_u32 s25, s25, 0
	v_and_b32_e32 v2, 0x1ff, v205
	v_mov_b32_e32 v3, v1
	s_mov_b64 s[30:31], 0
	v_mov_b32_e32 v30, v164
.Lvt_warm:
	v_ashrrev_i32_e32 v20, 6, v30
	v_mov_b64_e32 v[4:5], s[36:37]
	v_and_b32_e32 v21, -8, v20
	v_lshlrev_b32_e32 v0, 1, v2
	v_mad_i64_i32 v[4:5], s[0:1], v21, s77, v[4:5]
	v_lshl_add_u64 v[4:5], v[4:5], 0, v[0:1]
	v_add_co_u32_e32 v4, vcc, 0x1000, v4
	s_nop 1
	v_addc_co_u32_e32 v5, vcc, 0, v5, vcc
	global_load_ushort v33, v[4:5], off
	v_add_co_u32_e32 v4, vcc, 0x2800, v4
	s_nop 1
	v_addc_co_u32_e32 v5, vcc, 0, v5, vcc
	global_load_ushort v34, v[4:5], off
	v_add_co_u32_e32 v4, vcc, 0x2800, v4
	s_nop 1
	v_addc_co_u32_e32 v5, vcc, 0, v5, vcc
	global_load_ushort v35, v[4:5], off
	v_add_co_u32_e32 v4, vcc, 0x2800, v4
	s_nop 1
	v_addc_co_u32_e32 v5, vcc, 0, v5, vcc
	global_load_ushort v36, v[4:5], off
	v_add_co_u32_e32 v4, vcc, 0x2800, v4
	s_nop 1
	v_addc_co_u32_e32 v5, vcc, 0, v5, vcc
	global_load_ushort v37, v[4:5], off
	v_add_co_u32_e32 v4, vcc, 0x2800, v4
	s_nop 1
	v_addc_co_u32_e32 v5, vcc, 0, v5, vcc
	global_load_ushort v38, v[4:5], off
	v_add_co_u32_e32 v4, vcc, 0x2800, v4
	s_nop 1
	v_addc_co_u32_e32 v5, vcc, 0, v5, vcc
	global_load_ushort v39, v[4:5], off
	v_add_co_u32_e32 v4, vcc, 0x2800, v4
	s_nop 1
	v_addc_co_u32_e32 v5, vcc, 0, v5, vcc
	global_load_ushort v40, v[4:5], off
	v_add_u32_e32 v30, s38, v30
	s_mov_b32 s0, 0xbffff
	v_cmp_lt_i32_e32 vcc, s0, v30
	s_or_b64 s[30:31], vcc, s[30:31]
	s_andn2_b64 exec, exec, s[30:31]
	s_cbranch_execnz .Lvt_warm
	s_mov_b64 exec, s[28:29]
	s_mov_b64 s[30:31], 0
	s_mov_b32 s0, 0xc0000
	v_cmp_gt_i32_e32 vcc, s0, v164
	s_nop 1
	s_and_b64 exec, exec, vcc

.LBB0_610:
	s_or_b32 s48, s88, 1
	s_cmp_lt_i32 s48, s86
	s_cselect_b64 s[30:31], -1, 0
	s_and_b64 vcc, exec, s[30:31]
	s_cbranch_vccz .LBB0_612
	v_add_u32_e32 v0, 0xcc00, v211
	s_add_i32 vcc_lo, s88, 2
	s_cmp_lt_i32 vcc_lo, s86
	s_cbranch_scc1 .Lattn_w4_4
	s_waitcnt vmcnt(0)
	s_branch .Lattn_st_4
.Lattn_w4_4:
	s_waitcnt vmcnt(4)
.Lattn_st_4:
	ds_write_b128 v210, v[114:117] offset:34816
	ds_write2_b64 v0, v[118:119], v[120:121] offset1:1
	ds_write_b128 v210, v[122:125] offset:43520
	v_add_u32_e32 v0, 0xee00, v211
	ds_write2_b64 v0, v[126:127], v[128:129] offset1:1

.LBB0_632:
	s_cmp_lt_i32 s88, s87
	s_cbranch_scc0 .LBB0_634
	s_add_i32 vcc_lo, s88, 3
	s_cmp_lt_i32 vcc_lo, s86
	s_cbranch_scc1 .Lattn_w4_3
	s_waitcnt vmcnt(0)
	s_branch .Lattn_st_3

.Lattn_st_3:
	ds_write_b128 v210, v[130:133]
	ds_write2_b64 v212, v[134:135], v[136:137] offset1:1
	ds_write_b128 v210, v[138:141] offset:8704
	ds_write2_b64 v213, v[142:143], v[144:145] offset1:1

.LBB0_686:
	s_or_b32 s48, s81, 1
	s_cmp_lt_i32 s48, s86
	s_cselect_b64 s[30:31], -1, 0
	s_and_b64 vcc, exec, s[30:31]
	s_cbranch_vccz .LBB0_688
	v_add_u32_e32 v0, 0xcc00, v211
	s_add_i32 vcc_lo, s81, 2
	s_cmp_lt_i32 vcc_lo, s86
	s_cbranch_scc1 .Lattn_w4_2
	s_waitcnt vmcnt(0)
	s_branch .Lattn_st_2

.LBB0_708:
	s_cmp_lt_i32 s81, s87
	s_cbranch_scc0 .LBB0_710
	s_add_i32 vcc_lo, s81, 3
	s_cmp_lt_i32 vcc_lo, s86
	s_cbranch_scc1 .Lattn_w4_1
	s_waitcnt vmcnt(0)
	s_branch .Lattn_st_1
